# code placement: all twelve 32-MFMA segments of the GEMM K-loops start at byte phase 4 mod 8 (s_nop 0 pads ahead of the load segments' waits)
# speedup vs baseline: 1.0000x; 1.0000x over previous
.LBB0_189:
	s_add_u32 s30, s26, 0xfff80080
	s_addc_u32 s31, s27, -1
	s_and_b64 s[28:29], s[28:29], exec
	s_cselect_b32 s31, s19, s31
	s_cselect_b32 s30, s50, s30
	s_cselect_b32 s29, s17, s52
	s_cselect_b32 s28, s51, s25
	s_add_i32 s54, 0, 0x10000
	s_add_i32 s56, 0, 0x14000
	ds_read_b128 v[74:77], v238
	ds_read_b128 v[138:141], v238 offset:1024
	ds_read_b128 v[142:145], v238 offset:2048
	ds_read_b128 v[146:149], v238 offset:3072
	ds_read_b128 v[150:153], v238 offset:16384
	ds_read_b128 v[154:157], v238 offset:17408
	ds_read_b128 v[158:161], v238 offset:18432
	ds_read_b128 v[162:165], v238 offset:19456
	s_add_i32 m0, s33, 0xc000
	ds_read_b128 v[180:183], v193
	ds_read_b128 v[184:187], v193 offset:1024
	ds_read_b128 v[194:197], v193 offset:2048
	ds_read_b128 v[198:201], v193 offset:3072
	ds_read_b128 v[202:205], v193 offset:4096
	ds_read_b128 v[212:215], v193 offset:5120
	ds_read_b128 v[216:219], v193 offset:6144
	ds_read_b128 v[220:223], v193 offset:7168
	global_load_lds_dwordx4 v172, s[26:27]
	s_add_i32 m0, s33, 0xe000
	s_nop 0
	global_load_lds_dwordx4 v174, s[26:27]
	s_waitcnt vmcnt(8)
	s_waitcnt lgkmcnt(0)
	s_barrier
	v_mfma_f32_16x16x32_bf16 v[134:137], v[74:77], v[180:183], v[134:137]
	v_mfma_f32_16x16x32_bf16 v[126:129], v[142:145], v[180:183], v[126:129]
	v_mfma_f32_16x16x32_bf16 v[118:121], v[74:77], v[194:197], v[118:121]
	v_mfma_f32_16x16x32_bf16 v[110:113], v[142:145], v[194:197], v[110:113]
	v_mfma_f32_16x16x32_bf16 v[102:105], v[74:77], v[202:205], v[102:105]
	v_mfma_f32_16x16x32_bf16 v[94:97], v[142:145], v[202:205], v[94:97]
	v_mfma_f32_16x16x32_bf16 v[86:89], v[74:77], v[216:219], v[86:89]
	v_mfma_f32_16x16x32_bf16 v[78:81], v[142:145], v[216:219], v[78:81]
	v_mfma_f32_16x16x32_bf16 v[134:137], v[138:141], v[184:187], v[134:137]
	v_mfma_f32_16x16x32_bf16 v[126:129], v[146:149], v[184:187], v[126:129]
	v_mfma_f32_16x16x32_bf16 v[118:121], v[138:141], v[198:201], v[118:121]
	v_mfma_f32_16x16x32_bf16 v[110:113], v[146:149], v[198:201], v[110:113]
	v_mfma_f32_16x16x32_bf16 v[102:105], v[138:141], v[212:215], v[102:105]
	v_mfma_f32_16x16x32_bf16 v[94:97], v[146:149], v[212:215], v[94:97]
	v_mfma_f32_16x16x32_bf16 v[86:89], v[138:141], v[220:223], v[86:89]
	v_mfma_f32_16x16x32_bf16 v[78:81], v[146:149], v[220:223], v[78:81]
	v_mfma_f32_16x16x32_bf16 v[130:133], v[150:153], v[180:183], v[130:133]
	v_mfma_f32_16x16x32_bf16 v[122:125], v[158:161], v[180:183], v[122:125]
	v_mfma_f32_16x16x32_bf16 v[114:117], v[150:153], v[194:197], v[114:117]
	v_mfma_f32_16x16x32_bf16 v[106:109], v[158:161], v[194:197], v[106:109]
	v_mfma_f32_16x16x32_bf16 v[98:101], v[150:153], v[202:205], v[98:101]
	v_mfma_f32_16x16x32_bf16 v[90:93], v[158:161], v[202:205], v[90:93]
	v_mfma_f32_16x16x32_bf16 v[82:85], v[150:153], v[216:219], v[82:85]
	v_mfma_f32_16x16x32_bf16 v[70:73], v[158:161], v[216:219], v[70:73]
	v_mfma_f32_16x16x32_bf16 v[130:133], v[154:157], v[184:187], v[130:133]
	v_mfma_f32_16x16x32_bf16 v[122:125], v[162:165], v[184:187], v[122:125]
	v_mfma_f32_16x16x32_bf16 v[114:117], v[154:157], v[198:201], v[114:117]
	v_mfma_f32_16x16x32_bf16 v[106:109], v[162:165], v[198:201], v[106:109]
	v_mfma_f32_16x16x32_bf16 v[98:101], v[154:157], v[212:215], v[98:101]
	v_mfma_f32_16x16x32_bf16 v[90:93], v[162:165], v[212:215], v[90:93]
	v_mfma_f32_16x16x32_bf16 v[82:85], v[154:157], v[220:223], v[82:85]
	v_mfma_f32_16x16x32_bf16 v[70:73], v[162:165], v[220:223], v[70:73]
	s_barrier
	s_add_i32 s54, s54, s35
	s_mov_b32 m0, s54
	ds_read_b128 v[194:197], v193 offset:16384
	ds_read_b128 v[198:201], v193 offset:17408
	ds_read_b128 v[202:205], v193 offset:18432
	ds_read_b128 v[212:215], v193 offset:19456
	ds_read_b128 v[216:219], v193 offset:20480
	ds_read_b128 v[220:223], v193 offset:21504
	ds_read_b128 v[224:227], v193 offset:22528
	ds_read_b128 v[228:231], v193 offset:23552
	global_load_lds_dwordx4 v4, s[28:29]
	s_add_i32 m0, s54, 0x2000
	s_add_u32 s54, s28, 0x80000
	s_addc_u32 s55, s29, 0
	global_load_lds_dwordx4 v2, s[28:29]
	s_add_i32 s56, s56, s35
	s_mov_b32 m0, s56
	s_nop 0
	global_load_lds_dwordx4 v4, s[54:55]
	s_add_i32 m0, s56, 0x2000
	s_nop 0
	global_load_lds_dwordx4 v2, s[54:55]
	s_mov_b32 m0, s33
	s_nop 0
	global_load_lds_dwordx4 v168, s[30:31]
	s_mov_b32 m0, s38
	s_nop 0
	global_load_lds_dwordx4 v166, s[30:31]
	s_nop 0
	s_waitcnt vmcnt(8)
	s_waitcnt lgkmcnt(0)
	s_barrier
	v_mfma_f32_16x16x32_bf16 v[66:69], v[74:77], v[194:197], v[66:69]
	v_mfma_f32_16x16x32_bf16 v[58:61], v[142:145], v[194:197], v[58:61]
	v_mfma_f32_16x16x32_bf16 v[50:53], v[74:77], v[202:205], v[50:53]
	v_mfma_f32_16x16x32_bf16 v[42:45], v[142:145], v[202:205], v[42:45]
	v_mfma_f32_16x16x32_bf16 v[248:251], v[74:77], v[216:219], v[34:37]
	v_mfma_f32_16x16x32_bf16 v[206:209], v[142:145], v[216:219], v[26:29]
	v_mfma_f32_16x16x32_bf16 v[74:77], v[74:77], v[224:227], v[18:21]
	v_mfma_f32_16x16x32_bf16 v[142:145], v[142:145], v[224:227], v[10:13]
	v_mfma_f32_16x16x32_bf16 v[10:13], v[138:141], v[198:201], v[66:69]
	v_mfma_f32_16x16x32_bf16 v[18:21], v[146:149], v[198:201], v[58:61]
	v_mfma_f32_16x16x32_bf16 v[26:29], v[138:141], v[212:215], v[50:53]
	v_mfma_f32_16x16x32_bf16 v[34:37], v[146:149], v[212:215], v[42:45]
	v_mfma_f32_16x16x32_bf16 v[42:45], v[138:141], v[220:223], v[248:251]
	v_mfma_f32_16x16x32_bf16 v[50:53], v[146:149], v[220:223], v[206:209]
	v_mfma_f32_16x16x32_bf16 v[58:61], v[138:141], v[228:231], v[74:77]
	v_mfma_f32_16x16x32_bf16 v[66:69], v[146:149], v[228:231], v[142:145]
	v_mfma_f32_16x16x32_bf16 v[62:65], v[150:153], v[194:197], v[62:65]
	v_mfma_f32_16x16x32_bf16 v[54:57], v[158:161], v[194:197], v[54:57]
	v_mfma_f32_16x16x32_bf16 v[46:49], v[150:153], v[202:205], v[46:49]
	v_mfma_f32_16x16x32_bf16 v[38:41], v[158:161], v[202:205], v[38:41]
	v_mfma_f32_16x16x32_bf16 v[74:77], v[150:153], v[216:219], v[30:33]
	v_mfma_f32_16x16x32_bf16 v[138:141], v[158:161], v[216:219], v[22:25]
	v_mfma_f32_16x16x32_bf16 v[142:145], v[150:153], v[224:227], v[14:17]
	v_mfma_f32_16x16x32_bf16 v[146:149], v[158:161], v[224:227], v[6:9]
	v_mfma_f32_16x16x32_bf16 v[6:9], v[154:157], v[198:201], v[62:65]
	v_mfma_f32_16x16x32_bf16 v[14:17], v[162:165], v[198:201], v[54:57]
	v_mfma_f32_16x16x32_bf16 v[22:25], v[154:157], v[212:215], v[46:49]
	v_mfma_f32_16x16x32_bf16 v[30:33], v[162:165], v[212:215], v[38:41]
	v_mfma_f32_16x16x32_bf16 v[38:41], v[154:157], v[220:223], v[74:77]
	v_mfma_f32_16x16x32_bf16 v[46:49], v[162:165], v[220:223], v[138:141]
	v_mfma_f32_16x16x32_bf16 v[54:57], v[154:157], v[228:231], v[142:145]
	v_mfma_f32_16x16x32_bf16 v[62:65], v[162:165], v[228:231], v[146:149]
	s_barrier
	ds_read_b128 v[158:161], v238 offset:32768
	ds_read_b128 v[150:153], v238 offset:33792
	ds_read_b128 v[162:165], v238 offset:34816
	ds_read_b128 v[154:157], v238 offset:35840
	ds_read_b128 v[142:145], v238 offset:49152
	ds_read_b128 v[74:77], v238 offset:50176
	ds_read_b128 v[146:149], v238 offset:51200
	ds_read_b128 v[138:141], v238 offset:52224
	s_add_u32 s30, s30, 0x80000
	s_addc_u32 s31, s31, 0
	s_mov_b32 m0, s39
	ds_read_b128 v[194:197], v193 offset:32768
	ds_read_b128 v[198:201], v193 offset:33792
	ds_read_b128 v[202:205], v193 offset:34816
	ds_read_b128 v[206:209], v193 offset:35840
	ds_read_b128 v[212:215], v193 offset:36864
	ds_read_b128 v[216:219], v193 offset:37888
	ds_read_b128 v[220:223], v193 offset:38912
	ds_read_b128 v[224:227], v193 offset:39936
	global_load_lds_dwordx4 v168, s[30:31]
	s_mov_b32 m0, s40
	s_nop 0
	global_load_lds_dwordx4 v166, s[30:31]
	s_waitcnt vmcnt(8)
	s_waitcnt lgkmcnt(0)
	s_barrier
	v_mfma_f32_16x16x32_bf16 v[134:137], v[158:161], v[194:197], v[134:137]
	v_mfma_f32_16x16x32_bf16 v[126:129], v[162:165], v[194:197], v[126:129]
	v_mfma_f32_16x16x32_bf16 v[118:121], v[158:161], v[202:205], v[118:121]
	v_mfma_f32_16x16x32_bf16 v[110:113], v[162:165], v[202:205], v[110:113]
	v_mfma_f32_16x16x32_bf16 v[102:105], v[158:161], v[212:215], v[102:105]
	v_mfma_f32_16x16x32_bf16 v[94:97], v[162:165], v[212:215], v[94:97]
	v_mfma_f32_16x16x32_bf16 v[86:89], v[158:161], v[220:223], v[86:89]
	v_mfma_f32_16x16x32_bf16 v[78:81], v[162:165], v[220:223], v[78:81]
	v_mfma_f32_16x16x32_bf16 v[134:137], v[150:153], v[198:201], v[134:137]
	v_mfma_f32_16x16x32_bf16 v[126:129], v[154:157], v[198:201], v[126:129]
	v_mfma_f32_16x16x32_bf16 v[118:121], v[150:153], v[206:209], v[118:121]
	v_mfma_f32_16x16x32_bf16 v[110:113], v[154:157], v[206:209], v[110:113]
	v_mfma_f32_16x16x32_bf16 v[102:105], v[150:153], v[216:219], v[102:105]
	v_mfma_f32_16x16x32_bf16 v[94:97], v[154:157], v[216:219], v[94:97]
	v_mfma_f32_16x16x32_bf16 v[86:89], v[150:153], v[224:227], v[86:89]
	v_mfma_f32_16x16x32_bf16 v[78:81], v[154:157], v[224:227], v[78:81]
	v_mfma_f32_16x16x32_bf16 v[130:133], v[142:145], v[194:197], v[130:133]
	v_mfma_f32_16x16x32_bf16 v[122:125], v[146:149], v[194:197], v[122:125]
	v_mfma_f32_16x16x32_bf16 v[114:117], v[142:145], v[202:205], v[114:117]
	v_mfma_f32_16x16x32_bf16 v[106:109], v[146:149], v[202:205], v[106:109]
	v_mfma_f32_16x16x32_bf16 v[98:101], v[142:145], v[212:215], v[98:101]
	v_mfma_f32_16x16x32_bf16 v[90:93], v[146:149], v[212:215], v[90:93]
	v_mfma_f32_16x16x32_bf16 v[82:85], v[142:145], v[220:223], v[82:85]
	v_mfma_f32_16x16x32_bf16 v[70:73], v[146:149], v[220:223], v[70:73]
	v_mfma_f32_16x16x32_bf16 v[130:133], v[74:77], v[198:201], v[130:133]
	v_mfma_f32_16x16x32_bf16 v[122:125], v[138:141], v[198:201], v[122:125]
	v_mfma_f32_16x16x32_bf16 v[114:117], v[74:77], v[206:209], v[114:117]
	v_mfma_f32_16x16x32_bf16 v[106:109], v[138:141], v[206:209], v[106:109]
	v_mfma_f32_16x16x32_bf16 v[98:101], v[74:77], v[216:219], v[98:101]
	v_mfma_f32_16x16x32_bf16 v[90:93], v[138:141], v[216:219], v[90:93]
	v_mfma_f32_16x16x32_bf16 v[82:85], v[74:77], v[224:227], v[82:85]
	v_mfma_f32_16x16x32_bf16 v[70:73], v[138:141], v[224:227], v[70:73]
	s_barrier
	s_and_b64 vcc, exec, s[6:7]
	s_cbranch_vccnz .LBB0_186
	v_ffbh_u32_e32 v194, v177
	v_min_u32_e32 v196, 32, v194
	v_lshlrev_b64 v[194:195], v196, v[176:177]
	v_min_u32_e32 v194, 1, v194
	v_or_b32_e32 v194, v195, v194
	v_cvt_f32_u32_e32 v194, v194
	v_sub_u32_e32 v195, 32, v196
	v_ldexp_f32 v194, v194, v195
	v_mul_f32_e32 v194, 0x33800000, v194
	v_fmamk_f32 v194, v194, 0x3a000000, v232
	v_rsq_f32_e32 v194, v194
	ds_write_b32 v190, v194
	s_branch .LBB0_186

.LBB0_211:
	s_add_u32 s38, s8, 0xfff80080
	s_addc_u32 s39, s9, -1
	s_and_b64 s[34:35], s[34:35], exec
	s_cselect_b32 s39, s25, s39
	s_cselect_b32 s38, s62, s38
	s_cselect_b32 s35, s23, s64
	s_cselect_b32 s34, s63, s31
	s_add_i32 s66, 0, 0x10000
	s_add_i32 s68, 0, 0x14000
	ds_read_b128 v[134:137], v173
	ds_read_b128 v[138:141], v173 offset:1024
	ds_read_b128 v[142:145], v173 offset:2048
	ds_read_b128 v[146:149], v173 offset:3072
	ds_read_b128 v[150:153], v173 offset:16384
	ds_read_b128 v[154:157], v173 offset:17408
	ds_read_b128 v[158:161], v173 offset:18432
	ds_read_b128 v[162:165], v173 offset:19456
	s_add_i32 m0, s33, 0xc000
	ds_read_b128 v[180:183], v213
	ds_read_b128 v[184:187], v213 offset:1024
	ds_read_b128 v[188:191], v213 offset:2048
	ds_read_b128 v[192:195], v213 offset:3072
	ds_read_b128 v[196:199], v213 offset:4096
	ds_read_b128 v[206:209], v213 offset:5120
	ds_read_b128 v[214:217], v213 offset:6144
	ds_read_b128 v[218:221], v213 offset:7168
	global_load_lds_dwordx4 v172, s[8:9]
	s_add_i32 m0, s33, 0xe000
	s_nop 0
	global_load_lds_dwordx4 v174, s[8:9]
	s_waitcnt vmcnt(8)
	s_waitcnt lgkmcnt(0)
	s_barrier
	v_mfma_f32_16x16x32_bf16 v[130:133], v[134:137], v[180:183], v[130:133]
	v_mfma_f32_16x16x32_bf16 v[126:129], v[142:145], v[180:183], v[126:129]
	v_mfma_f32_16x16x32_bf16 v[122:125], v[134:137], v[188:191], v[122:125]
	v_mfma_f32_16x16x32_bf16 v[114:117], v[142:145], v[188:191], v[114:117]
	v_mfma_f32_16x16x32_bf16 v[106:109], v[134:137], v[196:199], v[106:109]
	v_mfma_f32_16x16x32_bf16 v[98:101], v[142:145], v[196:199], v[98:101]
	v_mfma_f32_16x16x32_bf16 v[90:93], v[134:137], v[214:217], v[90:93]
	v_mfma_f32_16x16x32_bf16 v[82:85], v[142:145], v[214:217], v[82:85]
	v_mfma_f32_16x16x32_bf16 v[130:133], v[138:141], v[184:187], v[130:133]
	v_mfma_f32_16x16x32_bf16 v[126:129], v[146:149], v[184:187], v[126:129]
	v_mfma_f32_16x16x32_bf16 v[122:125], v[138:141], v[192:195], v[122:125]
	v_mfma_f32_16x16x32_bf16 v[114:117], v[146:149], v[192:195], v[114:117]
	v_mfma_f32_16x16x32_bf16 v[106:109], v[138:141], v[206:209], v[106:109]
	v_mfma_f32_16x16x32_bf16 v[98:101], v[146:149], v[206:209], v[98:101]
	v_mfma_f32_16x16x32_bf16 v[90:93], v[138:141], v[218:221], v[90:93]
	v_mfma_f32_16x16x32_bf16 v[82:85], v[146:149], v[218:221], v[82:85]
	v_mfma_f32_16x16x32_bf16 v[118:121], v[150:153], v[180:183], v[118:121]
	v_mfma_f32_16x16x32_bf16 v[110:113], v[158:161], v[180:183], v[110:113]
	v_mfma_f32_16x16x32_bf16 v[102:105], v[150:153], v[188:191], v[102:105]
	v_mfma_f32_16x16x32_bf16 v[94:97], v[158:161], v[188:191], v[94:97]
	v_mfma_f32_16x16x32_bf16 v[86:89], v[150:153], v[196:199], v[86:89]
	v_mfma_f32_16x16x32_bf16 v[78:81], v[158:161], v[196:199], v[78:81]
	v_mfma_f32_16x16x32_bf16 v[74:77], v[150:153], v[214:217], v[74:77]
	v_mfma_f32_16x16x32_bf16 v[70:73], v[158:161], v[214:217], v[70:73]
	v_mfma_f32_16x16x32_bf16 v[118:121], v[154:157], v[184:187], v[118:121]
	v_mfma_f32_16x16x32_bf16 v[110:113], v[162:165], v[184:187], v[110:113]
	v_mfma_f32_16x16x32_bf16 v[102:105], v[154:157], v[192:195], v[102:105]
	v_mfma_f32_16x16x32_bf16 v[94:97], v[162:165], v[192:195], v[94:97]
	v_mfma_f32_16x16x32_bf16 v[86:89], v[154:157], v[206:209], v[86:89]
	v_mfma_f32_16x16x32_bf16 v[78:81], v[162:165], v[206:209], v[78:81]
	v_mfma_f32_16x16x32_bf16 v[74:77], v[154:157], v[218:221], v[74:77]
	v_mfma_f32_16x16x32_bf16 v[70:73], v[162:165], v[218:221], v[70:73]
	s_barrier
	s_add_i32 s66, s66, s45
	s_mov_b32 m0, s66
	ds_read_b128 v[188:191], v213 offset:16384
	ds_read_b128 v[192:195], v213 offset:17408
	ds_read_b128 v[196:199], v213 offset:18432
	ds_read_b128 v[206:209], v213 offset:19456
	ds_read_b128 v[214:217], v213 offset:20480
	ds_read_b128 v[218:221], v213 offset:21504
	ds_read_b128 v[222:225], v213 offset:22528
	ds_read_b128 v[226:229], v213 offset:23552
	global_load_lds_dwordx4 v4, s[34:35]
	s_add_i32 m0, s66, 0x2000
	s_add_u32 s66, s34, 0x80000
	s_addc_u32 s67, s35, 0
	global_load_lds_dwordx4 v2, s[34:35]
	s_add_i32 s68, s68, s45
	s_mov_b32 m0, s68
	s_nop 0
	global_load_lds_dwordx4 v4, s[66:67]
	s_add_i32 m0, s68, 0x2000
	s_nop 0
	global_load_lds_dwordx4 v2, s[66:67]
	s_mov_b32 m0, s33
	s_nop 0
	global_load_lds_dwordx4 v168, s[38:39]
	s_mov_b32 m0, s46
	s_nop 0
	global_load_lds_dwordx4 v166, s[38:39]
	s_nop 0
	s_waitcnt vmcnt(8)
	s_waitcnt lgkmcnt(0)
	s_barrier
	v_mfma_f32_16x16x32_bf16 v[66:69], v[134:137], v[188:191], v[66:69]
	v_mfma_f32_16x16x32_bf16 v[62:65], v[142:145], v[188:191], v[62:65]
	v_mfma_f32_16x16x32_bf16 v[58:61], v[134:137], v[196:199], v[58:61]
	v_mfma_f32_16x16x32_bf16 v[50:53], v[142:145], v[196:199], v[50:53]
	v_mfma_f32_16x16x32_bf16 v[248:251], v[134:137], v[214:217], v[42:45]
	v_mfma_f32_16x16x32_bf16 v[236:239], v[142:145], v[214:217], v[34:37]
	v_mfma_f32_16x16x32_bf16 v[134:137], v[134:137], v[222:225], v[26:29]
	v_mfma_f32_16x16x32_bf16 v[142:145], v[142:145], v[222:225], v[18:21]
	v_mfma_f32_16x16x32_bf16 v[18:21], v[138:141], v[192:195], v[66:69]
	v_mfma_f32_16x16x32_bf16 v[26:29], v[146:149], v[192:195], v[62:65]
	v_mfma_f32_16x16x32_bf16 v[34:37], v[138:141], v[206:209], v[58:61]
	v_mfma_f32_16x16x32_bf16 v[42:45], v[146:149], v[206:209], v[50:53]
	v_mfma_f32_16x16x32_bf16 v[50:53], v[138:141], v[218:221], v[248:251]
	v_mfma_f32_16x16x32_bf16 v[58:61], v[146:149], v[218:221], v[236:239]
	v_mfma_f32_16x16x32_bf16 v[62:65], v[138:141], v[226:229], v[134:137]
	v_mfma_f32_16x16x32_bf16 v[66:69], v[146:149], v[226:229], v[142:145]
	v_mfma_f32_16x16x32_bf16 v[54:57], v[150:153], v[188:191], v[54:57]
	v_mfma_f32_16x16x32_bf16 v[46:49], v[158:161], v[188:191], v[46:49]
	v_mfma_f32_16x16x32_bf16 v[38:41], v[150:153], v[196:199], v[38:41]
	v_mfma_f32_16x16x32_bf16 v[30:33], v[158:161], v[196:199], v[30:33]
	v_mfma_f32_16x16x32_bf16 v[134:137], v[150:153], v[214:217], v[22:25]
	v_mfma_f32_16x16x32_bf16 v[138:141], v[158:161], v[214:217], v[14:17]
	v_mfma_f32_16x16x32_bf16 v[142:145], v[150:153], v[222:225], v[10:13]
	v_mfma_f32_16x16x32_bf16 v[146:149], v[158:161], v[222:225], v[6:9]
	v_mfma_f32_16x16x32_bf16 v[6:9], v[154:157], v[192:195], v[54:57]
	v_mfma_f32_16x16x32_bf16 v[10:13], v[162:165], v[192:195], v[46:49]
	v_mfma_f32_16x16x32_bf16 v[14:17], v[154:157], v[206:209], v[38:41]
	v_mfma_f32_16x16x32_bf16 v[22:25], v[162:165], v[206:209], v[30:33]
	v_mfma_f32_16x16x32_bf16 v[30:33], v[154:157], v[218:221], v[134:137]
	v_mfma_f32_16x16x32_bf16 v[38:41], v[162:165], v[218:221], v[138:141]
	v_mfma_f32_16x16x32_bf16 v[46:49], v[154:157], v[226:229], v[142:145]
	v_mfma_f32_16x16x32_bf16 v[54:57], v[162:165], v[226:229], v[146:149]
	s_barrier
	ds_read_b128 v[158:161], v173 offset:32768
	ds_read_b128 v[150:153], v173 offset:33792
	ds_read_b128 v[162:165], v173 offset:34816
	ds_read_b128 v[154:157], v173 offset:35840
	ds_read_b128 v[142:145], v173 offset:49152
	ds_read_b128 v[134:137], v173 offset:50176
	ds_read_b128 v[146:149], v173 offset:51200
	ds_read_b128 v[138:141], v173 offset:52224
	s_add_u32 s38, s38, 0x80000
	s_addc_u32 s39, s39, 0
	s_mov_b32 m0, s47
	ds_read_b128 v[188:191], v213 offset:32768
	ds_read_b128 v[192:195], v213 offset:33792
	ds_read_b128 v[196:199], v213 offset:34816
	ds_read_b128 v[206:209], v213 offset:35840
	ds_read_b128 v[214:217], v213 offset:36864
	ds_read_b128 v[218:221], v213 offset:37888
	ds_read_b128 v[222:225], v213 offset:38912
	ds_read_b128 v[226:229], v213 offset:39936
	global_load_lds_dwordx4 v168, s[38:39]
	s_mov_b32 m0, s48
	s_nop 0
	global_load_lds_dwordx4 v166, s[38:39]
	s_waitcnt vmcnt(8)
	s_waitcnt lgkmcnt(0)
	s_barrier
	v_mfma_f32_16x16x32_bf16 v[130:133], v[158:161], v[188:191], v[130:133]
	v_mfma_f32_16x16x32_bf16 v[126:129], v[162:165], v[188:191], v[126:129]
	v_mfma_f32_16x16x32_bf16 v[122:125], v[158:161], v[196:199], v[122:125]
	v_mfma_f32_16x16x32_bf16 v[114:117], v[162:165], v[196:199], v[114:117]
	v_mfma_f32_16x16x32_bf16 v[106:109], v[158:161], v[214:217], v[106:109]
	v_mfma_f32_16x16x32_bf16 v[98:101], v[162:165], v[214:217], v[98:101]
	v_mfma_f32_16x16x32_bf16 v[90:93], v[158:161], v[222:225], v[90:93]
	v_mfma_f32_16x16x32_bf16 v[82:85], v[162:165], v[222:225], v[82:85]
	v_mfma_f32_16x16x32_bf16 v[130:133], v[150:153], v[192:195], v[130:133]
	v_mfma_f32_16x16x32_bf16 v[126:129], v[154:157], v[192:195], v[126:129]
	v_mfma_f32_16x16x32_bf16 v[122:125], v[150:153], v[206:209], v[122:125]
	v_mfma_f32_16x16x32_bf16 v[114:117], v[154:157], v[206:209], v[114:117]
	v_mfma_f32_16x16x32_bf16 v[106:109], v[150:153], v[218:221], v[106:109]
	v_mfma_f32_16x16x32_bf16 v[98:101], v[154:157], v[218:221], v[98:101]
	v_mfma_f32_16x16x32_bf16 v[90:93], v[150:153], v[226:229], v[90:93]
	v_mfma_f32_16x16x32_bf16 v[82:85], v[154:157], v[226:229], v[82:85]
	v_mfma_f32_16x16x32_bf16 v[118:121], v[142:145], v[188:191], v[118:121]
	v_mfma_f32_16x16x32_bf16 v[110:113], v[146:149], v[188:191], v[110:113]
	v_mfma_f32_16x16x32_bf16 v[102:105], v[142:145], v[196:199], v[102:105]
	v_mfma_f32_16x16x32_bf16 v[94:97], v[146:149], v[196:199], v[94:97]
	v_mfma_f32_16x16x32_bf16 v[86:89], v[142:145], v[214:217], v[86:89]
	v_mfma_f32_16x16x32_bf16 v[78:81], v[146:149], v[214:217], v[78:81]
	v_mfma_f32_16x16x32_bf16 v[74:77], v[142:145], v[222:225], v[74:77]
	v_mfma_f32_16x16x32_bf16 v[70:73], v[146:149], v[222:225], v[70:73]
	v_mfma_f32_16x16x32_bf16 v[118:121], v[134:137], v[192:195], v[118:121]
	v_mfma_f32_16x16x32_bf16 v[110:113], v[138:141], v[192:195], v[110:113]
	v_mfma_f32_16x16x32_bf16 v[102:105], v[134:137], v[206:209], v[102:105]
	v_mfma_f32_16x16x32_bf16 v[94:97], v[138:141], v[206:209], v[94:97]
	v_mfma_f32_16x16x32_bf16 v[86:89], v[134:137], v[218:221], v[86:89]
	v_mfma_f32_16x16x32_bf16 v[78:81], v[138:141], v[218:221], v[78:81]
	v_mfma_f32_16x16x32_bf16 v[74:77], v[134:137], v[226:229], v[74:77]
	v_mfma_f32_16x16x32_bf16 v[70:73], v[138:141], v[226:229], v[70:73]
	s_barrier
	s_and_b64 vcc, exec, s[6:7]
	s_cbranch_vccnz .LBB0_208
	v_ffbh_u32_e32 v188, v177
	v_min_u32_e32 v190, 32, v188
	v_lshlrev_b64 v[188:189], v190, v[176:177]
	v_min_u32_e32 v188, 1, v188
	v_or_b32_e32 v188, v189, v188
	v_cvt_f32_u32_e32 v188, v188
	v_sub_u32_e32 v189, 32, v190
	v_ldexp_f32 v188, v188, v189
	v_mul_f32_e32 v188, 0x33800000, v188
	v_fmamk_f32 v188, v188, 0x3a000000, v232
	v_rsq_f32_e32 v188, v188
	ds_write_b32 v204, v188
	s_branch .LBB0_208

.LBB0_497:
	s_add_i32 s56, s30, 2
	s_add_u32 s57, s28, 0x80
	s_addc_u32 s31, s29, 0
	s_add_i32 s60, 0, 0x10000
	s_cmp_eq_u32 s48, s30
	s_cselect_b32 s31, s15, s31
	s_cselect_b32 s30, s14, s57
	s_cselect_b32 s59, s27, s55
	s_cselect_b32 s58, s26, s54
	s_add_i32 s57, 0, 0x14000
	ds_read_b128 v[134:137], v238
	ds_read_b128 v[138:141], v238 offset:1024
	ds_read_b128 v[142:145], v238 offset:2048
	ds_read_b128 v[146:149], v238 offset:3072
	ds_read_b128 v[150:153], v238 offset:16384
	ds_read_b128 v[154:157], v238 offset:17408
	ds_read_b128 v[158:161], v238 offset:18432
	ds_read_b128 v[162:165], v238 offset:19456
	s_add_i32 m0, s41, 0xc000
	ds_read_b128 v[166:169], v251
	ds_read_b128 v[170:173], v251 offset:1024
	ds_read_b128 v[174:177], v251 offset:2048
	ds_read_b128 v[178:181], v251 offset:3072
	ds_read_b128 v[182:185], v251 offset:4096
	ds_read_b128 v[186:189], v251 offset:5120
	ds_read_b128 v[190:193], v251 offset:6144
	ds_read_b128 v[194:197], v251 offset:7168
	global_load_lds_dwordx4 v224, s[28:29]
	s_add_i32 m0, s41, 0xe000
	s_nop 0
	global_load_lds_dwordx4 v226, s[28:29]
	s_waitcnt vmcnt(8)
	s_waitcnt lgkmcnt(0)
	s_barrier
	v_mfma_f32_16x16x32_bf16 v[130:133], v[134:137], v[166:169], v[130:133]
	v_mfma_f32_16x16x32_bf16 v[126:129], v[142:145], v[166:169], v[126:129]
	v_mfma_f32_16x16x32_bf16 v[114:117], v[134:137], v[174:177], v[114:117]
	v_mfma_f32_16x16x32_bf16 v[110:113], v[142:145], v[174:177], v[110:113]
	v_mfma_f32_16x16x32_bf16 v[98:101], v[134:137], v[182:185], v[98:101]
	v_mfma_f32_16x16x32_bf16 v[94:97], v[142:145], v[182:185], v[94:97]
	v_mfma_f32_16x16x32_bf16 v[82:85], v[134:137], v[190:193], v[82:85]
	v_mfma_f32_16x16x32_bf16 v[78:81], v[142:145], v[190:193], v[78:81]
	v_mfma_f32_16x16x32_bf16 v[130:133], v[138:141], v[170:173], v[130:133]
	v_mfma_f32_16x16x32_bf16 v[126:129], v[146:149], v[170:173], v[126:129]
	v_mfma_f32_16x16x32_bf16 v[114:117], v[138:141], v[178:181], v[114:117]
	v_mfma_f32_16x16x32_bf16 v[110:113], v[146:149], v[178:181], v[110:113]
	v_mfma_f32_16x16x32_bf16 v[98:101], v[138:141], v[186:189], v[98:101]
	v_mfma_f32_16x16x32_bf16 v[94:97], v[146:149], v[186:189], v[94:97]
	v_mfma_f32_16x16x32_bf16 v[82:85], v[138:141], v[194:197], v[82:85]
	v_mfma_f32_16x16x32_bf16 v[78:81], v[146:149], v[194:197], v[78:81]
	v_mfma_f32_16x16x32_bf16 v[122:125], v[150:153], v[166:169], v[122:125]
	v_mfma_f32_16x16x32_bf16 v[118:121], v[158:161], v[166:169], v[118:121]
	v_mfma_f32_16x16x32_bf16 v[106:109], v[150:153], v[174:177], v[106:109]
	v_mfma_f32_16x16x32_bf16 v[102:105], v[158:161], v[174:177], v[102:105]
	v_mfma_f32_16x16x32_bf16 v[90:93], v[150:153], v[182:185], v[90:93]
	v_mfma_f32_16x16x32_bf16 v[86:89], v[158:161], v[182:185], v[86:89]
	v_mfma_f32_16x16x32_bf16 v[74:77], v[150:153], v[190:193], v[74:77]
	v_mfma_f32_16x16x32_bf16 v[70:73], v[158:161], v[190:193], v[70:73]
	v_mfma_f32_16x16x32_bf16 v[122:125], v[154:157], v[170:173], v[122:125]
	v_mfma_f32_16x16x32_bf16 v[118:121], v[162:165], v[170:173], v[118:121]
	v_mfma_f32_16x16x32_bf16 v[106:109], v[154:157], v[178:181], v[106:109]
	v_mfma_f32_16x16x32_bf16 v[102:105], v[162:165], v[178:181], v[102:105]
	v_mfma_f32_16x16x32_bf16 v[90:93], v[154:157], v[186:189], v[90:93]
	v_mfma_f32_16x16x32_bf16 v[86:89], v[162:165], v[186:189], v[86:89]
	v_mfma_f32_16x16x32_bf16 v[74:77], v[154:157], v[194:197], v[74:77]
	v_mfma_f32_16x16x32_bf16 v[70:73], v[162:165], v[194:197], v[70:73]
	s_barrier
	s_add_i32 s60, s60, s40
	s_mov_b32 m0, s60
	ds_read_b128 v[166:169], v251 offset:16384
	ds_read_b128 v[170:173], v251 offset:17408
	ds_read_b128 v[174:177], v251 offset:18432
	ds_read_b128 v[178:181], v251 offset:19456
	ds_read_b128 v[182:185], v251 offset:20480
	ds_read_b128 v[186:189], v251 offset:21504
	ds_read_b128 v[190:193], v251 offset:22528
	ds_read_b128 v[194:197], v251 offset:23552
	global_load_lds_dwordx4 v214, s[58:59]
	s_add_i32 m0, s60, 0x2000
	s_add_i32 s57, s57, s40
	global_load_lds_dwordx4 v2, s[58:59]
	s_add_u32 s58, s58, s76
	s_addc_u32 s59, s59, 0
	s_mov_b32 m0, s57
	s_nop 0
	global_load_lds_dwordx4 v214, s[58:59]
	s_add_i32 m0, s57, 0x2000
	s_nop 0
	global_load_lds_dwordx4 v2, s[58:59]
	s_mov_b32 m0, s41
	s_nop 0
	global_load_lds_dwordx4 v216, s[30:31]
	s_mov_b32 m0, s42
	s_nop 0
	global_load_lds_dwordx4 v212, s[30:31]
	s_waitcnt vmcnt(8)
	s_waitcnt lgkmcnt(0)
	s_barrier
	v_mfma_f32_16x16x32_bf16 v[66:69], v[134:137], v[166:169], v[66:69]
	v_mfma_f32_16x16x32_bf16 v[62:65], v[142:145], v[166:169], v[62:65]
	v_mfma_f32_16x16x32_bf16 v[50:53], v[134:137], v[174:177], v[50:53]
	v_mfma_f32_16x16x32_bf16 v[46:49], v[142:145], v[174:177], v[46:49]
	v_mfma_f32_16x16x32_bf16 v[34:37], v[134:137], v[182:185], v[34:37]
	v_mfma_f32_16x16x32_bf16 v[30:33], v[142:145], v[182:185], v[30:33]
	v_mfma_f32_16x16x32_bf16 v[18:21], v[134:137], v[190:193], v[18:21]
	v_mfma_f32_16x16x32_bf16 v[14:17], v[142:145], v[190:193], v[14:17]
	v_mfma_f32_16x16x32_bf16 v[66:69], v[138:141], v[170:173], v[66:69]
	v_mfma_f32_16x16x32_bf16 v[62:65], v[146:149], v[170:173], v[62:65]
	v_mfma_f32_16x16x32_bf16 v[50:53], v[138:141], v[178:181], v[50:53]
	v_mfma_f32_16x16x32_bf16 v[46:49], v[146:149], v[178:181], v[46:49]
	v_mfma_f32_16x16x32_bf16 v[34:37], v[138:141], v[186:189], v[34:37]
	v_mfma_f32_16x16x32_bf16 v[30:33], v[146:149], v[186:189], v[30:33]
	v_mfma_f32_16x16x32_bf16 v[18:21], v[138:141], v[194:197], v[18:21]
	v_mfma_f32_16x16x32_bf16 v[14:17], v[146:149], v[194:197], v[14:17]
	v_mfma_f32_16x16x32_bf16 v[58:61], v[150:153], v[166:169], v[58:61]
	v_mfma_f32_16x16x32_bf16 v[54:57], v[158:161], v[166:169], v[54:57]
	v_mfma_f32_16x16x32_bf16 v[42:45], v[150:153], v[174:177], v[42:45]
	v_mfma_f32_16x16x32_bf16 v[38:41], v[158:161], v[174:177], v[38:41]
	v_mfma_f32_16x16x32_bf16 v[26:29], v[150:153], v[182:185], v[26:29]
	v_mfma_f32_16x16x32_bf16 v[22:25], v[158:161], v[182:185], v[22:25]
	v_mfma_f32_16x16x32_bf16 v[10:13], v[150:153], v[190:193], v[10:13]
	v_mfma_f32_16x16x32_bf16 v[6:9], v[158:161], v[190:193], v[6:9]
	v_mfma_f32_16x16x32_bf16 v[58:61], v[154:157], v[170:173], v[58:61]
	v_mfma_f32_16x16x32_bf16 v[54:57], v[162:165], v[170:173], v[54:57]
	v_mfma_f32_16x16x32_bf16 v[42:45], v[154:157], v[178:181], v[42:45]
	v_mfma_f32_16x16x32_bf16 v[38:41], v[162:165], v[178:181], v[38:41]
	v_mfma_f32_16x16x32_bf16 v[26:29], v[154:157], v[186:189], v[26:29]
	v_mfma_f32_16x16x32_bf16 v[22:25], v[162:165], v[186:189], v[22:25]
	v_mfma_f32_16x16x32_bf16 v[10:13], v[154:157], v[194:197], v[10:13]
	v_mfma_f32_16x16x32_bf16 v[6:9], v[162:165], v[194:197], v[6:9]
	s_barrier
	ds_read_b128 v[134:137], v238 offset:32768
	ds_read_b128 v[138:141], v238 offset:33792
	ds_read_b128 v[142:145], v238 offset:34816
	ds_read_b128 v[146:149], v238 offset:35840
	ds_read_b128 v[150:153], v238 offset:49152
	ds_read_b128 v[154:157], v238 offset:50176
	ds_read_b128 v[158:161], v238 offset:51200
	ds_read_b128 v[162:165], v238 offset:52224
	s_add_u32 s30, s30, s76
	s_addc_u32 s31, s31, 0
	s_mov_b32 m0, s43
	ds_read_b128 v[166:169], v251 offset:32768
	ds_read_b128 v[170:173], v251 offset:33792
	ds_read_b128 v[174:177], v251 offset:34816
	ds_read_b128 v[178:181], v251 offset:35840
	ds_read_b128 v[182:185], v251 offset:36864
	ds_read_b128 v[186:189], v251 offset:37888
	ds_read_b128 v[190:193], v251 offset:38912
	ds_read_b128 v[194:197], v251 offset:39936
	global_load_lds_dwordx4 v216, s[30:31]
	s_mov_b32 m0, s44
	s_nop 0
	global_load_lds_dwordx4 v212, s[30:31]
	s_nop 0
	s_waitcnt vmcnt(8)
	s_waitcnt lgkmcnt(0)
	s_barrier
	v_mfma_f32_16x16x32_bf16 v[130:133], v[134:137], v[166:169], v[130:133]
	v_mfma_f32_16x16x32_bf16 v[126:129], v[142:145], v[166:169], v[126:129]
	v_mfma_f32_16x16x32_bf16 v[114:117], v[134:137], v[174:177], v[114:117]
	v_mfma_f32_16x16x32_bf16 v[110:113], v[142:145], v[174:177], v[110:113]
	v_mfma_f32_16x16x32_bf16 v[98:101], v[134:137], v[182:185], v[98:101]
	v_mfma_f32_16x16x32_bf16 v[94:97], v[142:145], v[182:185], v[94:97]
	v_mfma_f32_16x16x32_bf16 v[82:85], v[134:137], v[190:193], v[82:85]
	v_mfma_f32_16x16x32_bf16 v[78:81], v[142:145], v[190:193], v[78:81]
	v_mfma_f32_16x16x32_bf16 v[130:133], v[138:141], v[170:173], v[130:133]
	v_mfma_f32_16x16x32_bf16 v[126:129], v[146:149], v[170:173], v[126:129]
	v_mfma_f32_16x16x32_bf16 v[114:117], v[138:141], v[178:181], v[114:117]
	v_mfma_f32_16x16x32_bf16 v[110:113], v[146:149], v[178:181], v[110:113]
	v_mfma_f32_16x16x32_bf16 v[98:101], v[138:141], v[186:189], v[98:101]
	v_mfma_f32_16x16x32_bf16 v[94:97], v[146:149], v[186:189], v[94:97]
	v_mfma_f32_16x16x32_bf16 v[82:85], v[138:141], v[194:197], v[82:85]
	v_mfma_f32_16x16x32_bf16 v[78:81], v[146:149], v[194:197], v[78:81]
	v_mfma_f32_16x16x32_bf16 v[122:125], v[150:153], v[166:169], v[122:125]
	v_mfma_f32_16x16x32_bf16 v[118:121], v[158:161], v[166:169], v[118:121]
	v_mfma_f32_16x16x32_bf16 v[106:109], v[150:153], v[174:177], v[106:109]
	v_mfma_f32_16x16x32_bf16 v[102:105], v[158:161], v[174:177], v[102:105]
	v_mfma_f32_16x16x32_bf16 v[90:93], v[150:153], v[182:185], v[90:93]
	v_mfma_f32_16x16x32_bf16 v[86:89], v[158:161], v[182:185], v[86:89]
	v_mfma_f32_16x16x32_bf16 v[74:77], v[150:153], v[190:193], v[74:77]
	v_mfma_f32_16x16x32_bf16 v[70:73], v[158:161], v[190:193], v[70:73]
	v_mfma_f32_16x16x32_bf16 v[122:125], v[154:157], v[170:173], v[122:125]
	v_mfma_f32_16x16x32_bf16 v[118:121], v[162:165], v[170:173], v[118:121]
	v_mfma_f32_16x16x32_bf16 v[106:109], v[154:157], v[178:181], v[106:109]
	v_mfma_f32_16x16x32_bf16 v[102:105], v[162:165], v[178:181], v[102:105]
	v_mfma_f32_16x16x32_bf16 v[90:93], v[154:157], v[186:189], v[90:93]
	v_mfma_f32_16x16x32_bf16 v[86:89], v[162:165], v[186:189], v[86:89]
	v_mfma_f32_16x16x32_bf16 v[74:77], v[154:157], v[194:197], v[74:77]
	v_mfma_f32_16x16x32_bf16 v[70:73], v[162:165], v[194:197], v[70:73]
	s_barrier
	s_sub_u32 s98, s58, s76
	s_subb_u32 s99, s59, 0
	s_add_u32 s98, s98, 0x80
	s_addc_u32 s99, s99, 0
	s_add_i32 m0, s40, 0x18000
	ds_read_b128 v[166:169], v251 offset:49152
	ds_read_b128 v[170:173], v251 offset:50176
	ds_read_b128 v[174:177], v251 offset:51200
	ds_read_b128 v[178:181], v251 offset:52224
	ds_read_b128 v[182:185], v251 offset:53248
	ds_read_b128 v[186:189], v251 offset:54272
	ds_read_b128 v[190:193], v251 offset:55296
	ds_read_b128 v[194:197], v251 offset:56320
	global_load_lds_dwordx4 v214, s[98:99]
	s_add_i32 m0, s40, 0x1a000
	s_add_u32 s58, s58, 0x80
	s_addc_u32 s59, s59, 0
	global_load_lds_dwordx4 v2, s[98:99]
	s_add_i32 m0, s40, 0x1c000
	s_sub_u32 s30, s30, s76
	s_subb_u32 s31, s31, 0
	global_load_lds_dwordx4 v214, s[58:59]
	s_add_i32 m0, s40, 0x1e000
	s_add_u32 s30, s30, 0x80
	s_addc_u32 s31, s31, 0
	global_load_lds_dwordx4 v2, s[58:59]
	s_mov_b32 m0, s45
	s_nop 0
	global_load_lds_dwordx4 v216, s[30:31]
	s_mov_b32 m0, s46
	s_nop 0
	global_load_lds_dwordx4 v212, s[30:31]
	s_nop 0
	s_waitcnt vmcnt(8)
	s_waitcnt lgkmcnt(0)
	s_barrier
	v_mfma_f32_16x16x32_bf16 v[66:69], v[134:137], v[166:169], v[66:69]
	v_mfma_f32_16x16x32_bf16 v[62:65], v[142:145], v[166:169], v[62:65]
	v_mfma_f32_16x16x32_bf16 v[50:53], v[134:137], v[174:177], v[50:53]
	v_mfma_f32_16x16x32_bf16 v[46:49], v[142:145], v[174:177], v[46:49]
	v_mfma_f32_16x16x32_bf16 v[34:37], v[134:137], v[182:185], v[34:37]
	v_mfma_f32_16x16x32_bf16 v[30:33], v[142:145], v[182:185], v[30:33]
	v_mfma_f32_16x16x32_bf16 v[18:21], v[134:137], v[190:193], v[18:21]
	v_mfma_f32_16x16x32_bf16 v[14:17], v[142:145], v[190:193], v[14:17]
	v_mfma_f32_16x16x32_bf16 v[66:69], v[138:141], v[170:173], v[66:69]
	v_mfma_f32_16x16x32_bf16 v[62:65], v[146:149], v[170:173], v[62:65]
	v_mfma_f32_16x16x32_bf16 v[50:53], v[138:141], v[178:181], v[50:53]
	v_mfma_f32_16x16x32_bf16 v[46:49], v[146:149], v[178:181], v[46:49]
	v_mfma_f32_16x16x32_bf16 v[34:37], v[138:141], v[186:189], v[34:37]
	v_mfma_f32_16x16x32_bf16 v[30:33], v[146:149], v[186:189], v[30:33]
	v_mfma_f32_16x16x32_bf16 v[18:21], v[138:141], v[194:197], v[18:21]
	v_mfma_f32_16x16x32_bf16 v[14:17], v[146:149], v[194:197], v[14:17]
	v_mfma_f32_16x16x32_bf16 v[58:61], v[150:153], v[166:169], v[58:61]
	v_mfma_f32_16x16x32_bf16 v[54:57], v[158:161], v[166:169], v[54:57]
	v_mfma_f32_16x16x32_bf16 v[42:45], v[150:153], v[174:177], v[42:45]
	v_mfma_f32_16x16x32_bf16 v[38:41], v[158:161], v[174:177], v[38:41]
	v_mfma_f32_16x16x32_bf16 v[26:29], v[150:153], v[182:185], v[26:29]
	v_mfma_f32_16x16x32_bf16 v[22:25], v[158:161], v[182:185], v[22:25]
	v_mfma_f32_16x16x32_bf16 v[10:13], v[150:153], v[190:193], v[10:13]
	v_mfma_f32_16x16x32_bf16 v[6:9], v[158:161], v[190:193], v[6:9]
	v_mfma_f32_16x16x32_bf16 v[58:61], v[154:157], v[170:173], v[58:61]
	v_mfma_f32_16x16x32_bf16 v[54:57], v[162:165], v[170:173], v[54:57]
	v_mfma_f32_16x16x32_bf16 v[42:45], v[154:157], v[178:181], v[42:45]
	v_mfma_f32_16x16x32_bf16 v[38:41], v[162:165], v[178:181], v[38:41]
	v_mfma_f32_16x16x32_bf16 v[26:29], v[154:157], v[186:189], v[26:29]
	v_mfma_f32_16x16x32_bf16 v[22:25], v[162:165], v[186:189], v[22:25]
	v_mfma_f32_16x16x32_bf16 v[10:13], v[154:157], v[194:197], v[10:13]
	v_mfma_f32_16x16x32_bf16 v[6:9], v[162:165], v[194:197], v[6:9]
	s_barrier
	s_add_u32 s28, s28, 0x100
	s_addc_u32 s29, s29, 0
	s_add_u32 s54, s54, 0x100
	s_addc_u32 s55, s55, 0
	s_cmp_ge_u32 s56, s47
	s_mov_b32 s30, s56
	s_cbranch_scc0 .LBB0_497
	s_and_b64 vcc, exec, s[24:25]
	s_cbranch_vccz .LBB0_500
	s_barrier
